# on top of v4 (not v5): attention QK^T tiles issue their four K-fragment LDS reads together and wait with counted lgkmcnt per MFMA instead of read-wait-MFMA four times
# speedup vs baseline: 1.0080x; 1.0080x over previous
; #define LAS __attribute__((address_space(3)))
; __device__ __forceinline__ void attn_mfma(const GAS bf16* proj, GAS bf16* part, GAS float* lse, int TOKG, const GAS float* qgain, const GAS float* kgain, const GAS float* rel_bias,
;                                           unsigned char* lds, int tid, int lane, int wave, int bid, int G) {
;     ...
;         for (int j = 0; j < 5; ++j) if (j >= nskip) {
; #pragma unroll
;             for (int e = 0; e < 16; ++e) sc[j][e] = tb[32 * j + (e & 3) + 8 * (e >> 2)];
; #pragma unroll
;             for (int s = 0; s < 4; ++s) { const bf16x8 kf = *(const LAS bf16x8*)(L + ATT_KS + (32 * wave + 32 * j + c) * ATT_KSTR + (16 * s + 8 * hh) * 2);
;                 sc[j] = __builtin_amdgcn_mfma_f32_32x32x16_bf16(kf, qf[s], sc[j], 0, 0, 0); } }
.LBB0_301:
	ds_read2_b32 v[0:1], v197 offset0:160 offset1:161
	ds_read2_b32 v[2:3], v197 offset0:162 offset1:163
	ds_read2_b32 v[4:5], v197 offset0:168 offset1:169
	ds_read2_b32 v[6:7], v197 offset0:170 offset1:171
	ds_read_b128 v[96:99], v211
	ds_read2_b32 v[8:9], v197 offset0:176 offset1:177
	ds_read2_b32 v[10:11], v197 offset0:178 offset1:179
	ds_read2_b32 v[12:13], v197 offset0:184 offset1:185
	ds_read2_b32 v[14:15], v197 offset0:186 offset1:187
	ds_read_b128 v[100:103], v211 offset:32
	ds_read_b128 v[104:107], v211 offset:64
	ds_read_b128 v[108:111], v211 offset:96
	s_waitcnt lgkmcnt(3)
	v_mfma_f32_32x32x16_bf16 v[0:15], v[96:99], v[92:95], v[0:15]
	s_waitcnt lgkmcnt(2)
	v_mfma_f32_32x32x16_bf16 v[0:15], v[100:103], v[88:91], v[0:15]
	s_waitcnt lgkmcnt(1)
	v_mfma_f32_32x32x16_bf16 v[0:15], v[104:107], v[84:87], v[0:15]
	s_waitcnt lgkmcnt(0)
	v_mfma_f32_32x32x16_bf16 v[0:15], v[108:111], v[80:83], v[0:15]

; #define LAS __attribute__((address_space(3)))
; __device__ __forceinline__ void attn_mfma(const GAS bf16* proj, GAS bf16* part, GAS float* lse, int TOKG, const GAS float* qgain, const GAS float* kgain, const GAS float* rel_bias,
;                                           unsigned char* lds, int tid, int lane, int wave, int bid, int G) {
;     ...
;         const int nskip = (m0 == 0 && wave < 4) ? 4 - wave : 0;
; #pragma unroll
;         for (int j = 0; j < 5; ++j) if (j >= nskip) {
; #pragma unroll
;             for (int e = 0; e < 16; ++e) sc[j][e] = tb[32 * j + (e & 3) + 8 * (e >> 2)];
; #pragma unroll
;             for (int s = 0; s < 4; ++s) { const bf16x8 kf = *(const LAS bf16x8*)(L + ATT_KS + (32 * wave + 32 * j + c) * ATT_KSTR + (16 * s + 8 * hh) * 2);
;                 sc[j] = __builtin_amdgcn_mfma_f32_32x32x16_bf16(kf, qf[s], sc[j], 0, 0, 0); } }
.LBB0_310:
	ds_read2_b32 v[64:65], v197 offset0:32 offset1:33
	ds_read2_b32 v[66:67], v197 offset0:34 offset1:35
	ds_read2_b32 v[68:69], v197 offset0:40 offset1:41
	ds_read2_b32 v[70:71], v197 offset0:42 offset1:43
	ds_read_b128 v[96:99], v207
	ds_read2_b32 v[72:73], v197 offset0:48 offset1:49
	ds_read2_b32 v[74:75], v197 offset0:50 offset1:51
	ds_read2_b32 v[76:77], v197 offset0:56 offset1:57
	ds_read2_b32 v[78:79], v197 offset0:58 offset1:59
	ds_read_b128 v[100:103], v207 offset:32
	ds_read_b128 v[104:107], v207 offset:64
	ds_read_b128 v[108:111], v207 offset:96
	s_waitcnt lgkmcnt(3)
	v_mfma_f32_32x32x16_bf16 v[64:79], v[96:99], v[92:95], v[64:79]
	s_waitcnt lgkmcnt(2)
	v_mfma_f32_32x32x16_bf16 v[64:79], v[100:103], v[88:91], v[64:79]
	s_waitcnt lgkmcnt(1)
	v_mfma_f32_32x32x16_bf16 v[64:79], v[104:107], v[84:87], v[64:79]
	s_waitcnt lgkmcnt(0)
	v_mfma_f32_32x32x16_bf16 v[64:79], v[108:111], v[80:83], v[64:79]
	s_cmp_lt_i32 s18, 2
	s_cselect_b64 s[14:15], -1, 0
	s_cmp_gt_i32 s18, 1
	s_cbranch_scc1 .LBB0_298
.LBB0_311:
	ds_read2_b32 v[48:49], v197 offset0:64 offset1:65
	ds_read2_b32 v[50:51], v197 offset0:66 offset1:67
	ds_read2_b32 v[52:53], v197 offset0:72 offset1:73
	ds_read2_b32 v[54:55], v197 offset0:74 offset1:75
	ds_read_b128 v[96:99], v208
	ds_read2_b32 v[56:57], v197 offset0:80 offset1:81
	ds_read2_b32 v[58:59], v197 offset0:82 offset1:83
	ds_read2_b32 v[60:61], v197 offset0:88 offset1:89
	ds_read2_b32 v[62:63], v197 offset0:90 offset1:91
	ds_read_b128 v[100:103], v208 offset:32
	ds_read_b128 v[104:107], v208 offset:64
	ds_read_b128 v[108:111], v208 offset:96
	s_waitcnt lgkmcnt(3)
	v_mfma_f32_32x32x16_bf16 v[48:63], v[96:99], v[92:95], v[48:63]
	s_waitcnt lgkmcnt(2)
	v_mfma_f32_32x32x16_bf16 v[48:63], v[100:103], v[88:91], v[48:63]
	s_waitcnt lgkmcnt(1)
	v_mfma_f32_32x32x16_bf16 v[48:63], v[104:107], v[84:87], v[48:63]
	s_waitcnt lgkmcnt(0)
	v_mfma_f32_32x32x16_bf16 v[48:63], v[108:111], v[80:83], v[48:63]
	s_cmp_lt_i32 s18, 3
	s_cselect_b64 s[12:13], -1, 0
	s_cmp_gt_i32 s18, 2
	s_cbranch_scc1 .LBB0_299
.LBB0_312:
	ds_read2_b32 v[32:33], v197 offset0:96 offset1:97
	ds_read2_b32 v[34:35], v197 offset0:98 offset1:99
	ds_read2_b32 v[36:37], v197 offset0:104 offset1:105
	ds_read2_b32 v[38:39], v197 offset0:106 offset1:107
	ds_read_b128 v[96:99], v209
	ds_read2_b32 v[40:41], v197 offset0:112 offset1:113
	ds_read2_b32 v[42:43], v197 offset0:114 offset1:115
	ds_read2_b32 v[44:45], v197 offset0:120 offset1:121
	ds_read2_b32 v[46:47], v197 offset0:122 offset1:123
	ds_read_b128 v[100:103], v209 offset:32
	ds_read_b128 v[104:107], v209 offset:64
	ds_read_b128 v[108:111], v209 offset:96
	s_waitcnt lgkmcnt(3)
	v_mfma_f32_32x32x16_bf16 v[32:47], v[96:99], v[92:95], v[32:47]
	s_waitcnt lgkmcnt(2)
	v_mfma_f32_32x32x16_bf16 v[32:47], v[100:103], v[88:91], v[32:47]
	s_waitcnt lgkmcnt(1)
	v_mfma_f32_32x32x16_bf16 v[32:47], v[104:107], v[84:87], v[32:47]
	s_waitcnt lgkmcnt(0)
	v_mfma_f32_32x32x16_bf16 v[32:47], v[108:111], v[80:83], v[32:47]
	s_cmp_lt_i32 s18, 4
	s_cselect_b64 s[10:11], -1, 0
	s_cmp_gt_i32 s18, 3
	s_cbranch_scc1 .LBB0_300
.LBB0_313:
	ds_read2_b32 v[16:17], v197 offset0:128 offset1:129
	ds_read2_b32 v[18:19], v197 offset0:130 offset1:131
	ds_read2_b32 v[20:21], v197 offset0:136 offset1:137
	ds_read2_b32 v[22:23], v197 offset0:138 offset1:139
	ds_read_b128 v[96:99], v210
	ds_read2_b32 v[24:25], v197 offset0:144 offset1:145
	ds_read2_b32 v[26:27], v197 offset0:146 offset1:147
	ds_read2_b32 v[28:29], v197 offset0:152 offset1:153
	ds_read2_b32 v[30:31], v197 offset0:154 offset1:155
	ds_read_b128 v[100:103], v210 offset:32
	ds_read_b128 v[104:107], v210 offset:64
	ds_read_b128 v[108:111], v210 offset:96
	s_waitcnt lgkmcnt(3)
	v_mfma_f32_32x32x16_bf16 v[16:31], v[96:99], v[92:95], v[16:31]
	s_waitcnt lgkmcnt(2)
	v_mfma_f32_32x32x16_bf16 v[16:31], v[100:103], v[88:91], v[16:31]
	s_waitcnt lgkmcnt(1)
	v_mfma_f32_32x32x16_bf16 v[16:31], v[104:107], v[84:87], v[16:31]
	s_waitcnt lgkmcnt(0)
	v_mfma_f32_32x32x16_bf16 v[16:31], v[108:111], v[80:83], v[16:31]
	s_cmp_lt_i32 s18, 5
	s_cselect_b64 s[30:31], -1, 0
	s_cmp_gt_i32 s18, 4
	s_cbranch_scc0 .LBB0_301
	s_branch .LBB0_302
